# EpiAct hoist + EpiDown pipelined stats + P6/P1 first K iteration peeled with SrcC=0 (no accumulator zeroing)
# baseline (speedup 1.0000x reference)
; #define PG8_STAGE(bufoff, gbase, voff) do { _Pragma("unroll") for (int _i = 0; _i < 2; ++_i) \
;         __builtin_amdgcn_global_load_lds((const unsigned*)((const char*)(gbase) + (voff)[_i]), (PG8_LAS unsigned*)(lds + (bufoff) + ldsw + _i * 8192), 16, 0, 0); } while (0)
; #define PG8_LDA(dst, b, h) do { _Pragma("unroll") for (int m = 0; m < 4; ++m) _Pragma("unroll") for (int k = 0; k < 2; ++k) dst[m][k] = *(const PG8_LAS bf16x8*)(lds + PG8_SA(b, h) + aoff + m * 2048 + k * 1024); } while (0)
; #define PG8_LDB(dst, b, h) do { _Pragma("unroll") for (int n = 0; n < 2; ++n) _Pragma("unroll") for (int k = 0; k < 2; ++k) dst[n][k] = *(const PG8_LAS bf16x8*)(lds + PG8_SB(b, h) + boff + n * 2048 + k * 1024); } while (0)
; #define PG8_MMA(ai, bj, At, Bt) do { __builtin_amdgcn_s_setprio(1); _Pragma("unroll") for (int m = 0; m < 4; ++m) _Pragma("unroll") for (int n = 0; n < 2; ++n) _Pragma("unroll") for (int k = 0; k < 2; ++k) \
;         acc[ai][bj][m][n] = __builtin_amdgcn_mfma_f32_16x16x32_bf16(Bt[n][k], At[m][k], acc[ai][bj][m][n], 0, 0, 0); __builtin_amdgcn_s_setprio(0); } while (0)
; #define PG8_WAIT_V(n) asm volatile("s_waitcnt vmcnt(" #n ")" ::: "memory")
; #define PG8_WAIT_L(n) asm volatile("s_waitcnt lgkmcnt(" #n ")" ::: "memory")
; #define PG8_BAR __builtin_amdgcn_s_barrier()
; #define PG8_SCHED __builtin_amdgcn_sched_barrier(0)
; template <class Epi, class Sched, bool ALIGN_EPI = false, bool SP2 = false, bool AGM = false  >
; __device__ __forceinline__ void gemm_phase(PG8_LAS unsigned char* lds, const Gemm g, const Sched& S, const Epi& E) {
;     ...
;             PG8_LDB(B0, 0, 0); PG8_LDB(B1, 0, 1); PG8_SCHED; PG8_LDA(At, 0, 0); PG8_STAGE(PG8_SA(1, 1), a1 + hstepA, voffA);
;             PG8_WAIT_V(8); PG8_WAIT_L(0); PG8_BAR; PG8_MMA(0, 0, At, B0); PG8_MMA(0, 1, At, B1); PG8_BAR; PG8_SCHED;
;             PG8_LDA(At, 0, 1); PG8_STAGE(PG8_SB(0, 0), b2, voffB); PG8_STAGE(PG8_SB(0, 1), b2 + hstep, voffB); PG8_STAGE(PG8_SA(0, 0), a2, voffA);
;             PG8_WAIT_V(8); PG8_WAIT_L(0); PG8_BAR; PG8_MMA(1, 0, At, B0); PG8_MMA(1, 1, At, B1); PG8_BAR; PG8_SCHED;
;     ...
; #pragma unroll
;         for (int a = 0; a < 2; ++a)
; #pragma unroll
;             for (int b = 0; b < 2; ++b)
; #pragma unroll
;                 for (int m = 0; m < 4; ++m)
; #pragma unroll
;                     for (int n = 0; n < 2; ++n) acc[a][b][m][n] = (f32x4){0.f, 0.f, 0.f, 0.f};
.LBB0_136:
	s_ashr_i32 s15, s14, 31
	s_lshl_b64 s[16:17], s[14:15], 19
	s_add_u32 s16, s46, s16
	s_addc_u32 s17, s47, s17
	s_and_b64 s[18:19], s[0:1], exec
	s_cselect_b32 s15, s17, s23
	s_cselect_b32 s21, s16, s22
	s_ashr_i32 s13, s12, 31
	s_lshl_b64 s[18:19], s[12:13], 19
	s_add_u32 s18, s3, s18
	s_addc_u32 s19, s28, s19
	s_and_b64 s[26:27], s[0:1], exec
	s_cselect_b32 s13, s19, s25
	s_cselect_b32 s45, s18, s24
	s_add_u32 s22, s22, 0x40080
	s_addc_u32 s23, s23, 0
	s_add_u32 s53, s24, 0x100
	s_addc_u32 s54, s25, 0
	s_mov_b32 s55, -2
	ds_read_b128 v[150:153], v160
	ds_read_b128 v[164:167], v160 offset:1024
	ds_read_b128 v[168:171], v160 offset:2048
	ds_read_b128 v[172:175], v160 offset:3072
	ds_read_b128 v[176:179], v161
	ds_read_b128 v[180:183], v161 offset:1024
	ds_read_b128 v[184:187], v161 offset:2048
	ds_read_b128 v[188:191], v161 offset:3072
	s_add_u32 s24, s22, 0xfffc0080
	s_addc_u32 s25, s23, -1
	s_cmp_eq_u32 s55, 12
	s_cselect_b32 s27, s15, s25
	s_cselect_b32 s26, s21, s24
	s_cselect_b32 s25, s13, s54
	s_cselect_b32 s24, s45, s53
	v_lshl_add_u64 v[224:225], s[22:23], 0, v[142:143]
	s_add_i32 m0, s33, 0xc000
	ds_read_b128 v[192:195], v162
	ds_read_b128 v[196:199], v162 offset:1024
	ds_read_b128 v[200:203], v162 offset:2048
	ds_read_b128 v[204:207], v162 offset:3072
	ds_read_b128 v[208:211], v162 offset:4096
	ds_read_b128 v[212:215], v162 offset:5120
	ds_read_b128 v[216:219], v162 offset:6144
	ds_read_b128 v[220:223], v162 offset:7168
	global_load_lds_dwordx4 v[224:225], off
	v_lshl_add_u64 v[224:225], s[22:23], 0, v[144:145]
	s_add_i32 m0, s33, 0xe000
	s_nop 0
	global_load_lds_dwordx4 v[224:225], off
	s_waitcnt vmcnt(8)
	s_waitcnt lgkmcnt(0)
	s_barrier
	s_setprio 1
	s_waitcnt lgkmcnt(0)
	v_mfma_f32_16x16x32_bf16 v[126:129], v[150:153], v[192:195], 0
	v_mfma_f32_16x16x32_bf16 v[122:125], v[168:171], v[192:195], 0
	v_mfma_f32_16x16x32_bf16 v[114:117], v[150:153], v[200:203], 0
	v_mfma_f32_16x16x32_bf16 v[106:109], v[168:171], v[200:203], 0
	v_mfma_f32_16x16x32_bf16 v[102:105], v[150:153], v[208:211], 0
	v_mfma_f32_16x16x32_bf16 v[94:97], v[168:171], v[208:211], 0
	v_mfma_f32_16x16x32_bf16 v[86:89], v[150:153], v[216:219], 0
	v_mfma_f32_16x16x32_bf16 v[78:81], v[168:171], v[216:219], 0
	v_mfma_f32_16x16x32_bf16 v[126:129], v[164:167], v[196:199], v[126:129]
	v_mfma_f32_16x16x32_bf16 v[122:125], v[172:175], v[196:199], v[122:125]
	v_mfma_f32_16x16x32_bf16 v[114:117], v[164:167], v[204:207], v[114:117]
	v_mfma_f32_16x16x32_bf16 v[106:109], v[172:175], v[204:207], v[106:109]
	v_mfma_f32_16x16x32_bf16 v[102:105], v[164:167], v[212:215], v[102:105]
	v_mfma_f32_16x16x32_bf16 v[94:97], v[172:175], v[212:215], v[94:97]
	v_mfma_f32_16x16x32_bf16 v[86:89], v[164:167], v[220:223], v[86:89]
	v_mfma_f32_16x16x32_bf16 v[78:81], v[172:175], v[220:223], v[78:81]
	s_setprio 0
	s_setprio 1
	v_mfma_f32_16x16x32_bf16 v[118:121], v[176:179], v[192:195], 0
	v_mfma_f32_16x16x32_bf16 v[110:113], v[184:187], v[192:195], 0
	v_mfma_f32_16x16x32_bf16 v[98:101], v[176:179], v[200:203], 0
	v_mfma_f32_16x16x32_bf16 v[90:93], v[184:187], v[200:203], 0
	v_mfma_f32_16x16x32_bf16 v[82:85], v[176:179], v[208:211], 0
	v_mfma_f32_16x16x32_bf16 v[74:77], v[184:187], v[208:211], 0
	v_mfma_f32_16x16x32_bf16 v[70:73], v[176:179], v[216:219], 0
	v_mfma_f32_16x16x32_bf16 v[66:69], v[184:187], v[216:219], 0
	v_mfma_f32_16x16x32_bf16 v[118:121], v[180:183], v[196:199], v[118:121]
	v_mfma_f32_16x16x32_bf16 v[110:113], v[188:191], v[196:199], v[110:113]
	v_mfma_f32_16x16x32_bf16 v[98:101], v[180:183], v[204:207], v[98:101]
	v_mfma_f32_16x16x32_bf16 v[90:93], v[188:191], v[204:207], v[90:93]
	v_mfma_f32_16x16x32_bf16 v[82:85], v[180:183], v[212:215], v[82:85]
	v_mfma_f32_16x16x32_bf16 v[74:77], v[188:191], v[212:215], v[74:77]
	v_mfma_f32_16x16x32_bf16 v[70:73], v[180:183], v[220:223], v[70:73]
	v_mfma_f32_16x16x32_bf16 v[66:69], v[188:191], v[220:223], v[66:69]
	s_setprio 0
	s_barrier
	s_add_i32 s58, s41, s29
	v_lshl_add_u64 v[224:225], s[24:25], 0, v[134:135]
	s_mov_b32 m0, s58
	ds_read_b128 v[192:195], v162 offset:16384
	ds_read_b128 v[196:199], v162 offset:17408
	ds_read_b128 v[200:203], v162 offset:18432
	ds_read_b128 v[204:207], v162 offset:19456
	ds_read_b128 v[208:211], v162 offset:20480
	ds_read_b128 v[212:215], v162 offset:21504
	ds_read_b128 v[216:219], v162 offset:22528
	ds_read_b128 v[220:223], v162 offset:23552
	global_load_lds_dwordx4 v[224:225], off
	s_add_i32 m0, s58, 0x2000
	s_add_u32 s58, s24, 0x40000
	v_lshl_add_u64 v[226:227], s[24:25], 0, v[130:131]
	s_addc_u32 s59, s25, 0
	s_add_i32 s60, s42, s29
	global_load_lds_dwordx4 v[226:227], off
	v_lshl_add_u64 v[228:229], s[58:59], 0, v[134:135]
	s_mov_b32 m0, s60
	v_lshl_add_u64 v[230:231], s[26:27], 0, v[132:133]
	global_load_lds_dwordx4 v[228:229], off
	v_lshl_add_u64 v[228:229], s[58:59], 0, v[130:131]
	s_add_i32 m0, s60, 0x2000
	s_nop 0
	global_load_lds_dwordx4 v[228:229], off
	v_lshl_add_u64 v[228:229], s[26:27], 0, v[136:137]
	s_mov_b32 m0, s33
	s_nop 0
	global_load_lds_dwordx4 v[228:229], off
	s_mov_b32 m0, s34
	s_nop 0
	global_load_lds_dwordx4 v[230:231], off
	s_waitcnt vmcnt(8)
	s_waitcnt lgkmcnt(0)
	s_barrier
; #define PG8_STAGE(bufoff, gbase, voff) do { _Pragma("unroll") for (int _i = 0; _i < 2; ++_i) \
;         __builtin_amdgcn_global_load_lds((const unsigned*)((const char*)(gbase) + (voff)[_i]), (PG8_LAS unsigned*)(lds + (bufoff) + ldsw + _i * 8192), 16, 0, 0); } while (0)
; #define PG8_LDA(dst, b, h) do { _Pragma("unroll") for (int m = 0; m < 4; ++m) _Pragma("unroll") for (int k = 0; k < 2; ++k) dst[m][k] = *(const PG8_LAS bf16x8*)(lds + PG8_SA(b, h) + aoff + m * 2048 + k * 1024); } while (0)
; #define PG8_LDB(dst, b, h) do { _Pragma("unroll") for (int n = 0; n < 2; ++n) _Pragma("unroll") for (int k = 0; k < 2; ++k) dst[n][k] = *(const PG8_LAS bf16x8*)(lds + PG8_SB(b, h) + boff + n * 2048 + k * 1024); } while (0)
; #define PG8_MMA(ai, bj, At, Bt) do { __builtin_amdgcn_s_setprio(1); _Pragma("unroll") for (int m = 0; m < 4; ++m) _Pragma("unroll") for (int n = 0; n < 2; ++n) _Pragma("unroll") for (int k = 0; k < 2; ++k) \
;         acc[ai][bj][m][n] = __builtin_amdgcn_mfma_f32_16x16x32_bf16(Bt[n][k], At[m][k], acc[ai][bj][m][n], 0, 0, 0); __builtin_amdgcn_s_setprio(0); } while (0)
; #define PG8_WAIT_V(n) asm volatile("s_waitcnt vmcnt(" #n ")" ::: "memory")
; #define PG8_WAIT_L(n) asm volatile("s_waitcnt lgkmcnt(" #n ")" ::: "memory")
; #define PG8_BAR __builtin_amdgcn_s_barrier()
; #define PG8_SCHED __builtin_amdgcn_sched_barrier(0)
; template <class Epi, class Sched, bool ALIGN_EPI = false, bool SP2 = false, bool AGM = false  >
; __device__ __forceinline__ void gemm_phase(PG8_LAS unsigned char* lds, const Gemm g, const Sched& S, const Epi& E) {
;     ...
;             PG8_WAIT_V(8); PG8_WAIT_L(0); PG8_BAR; PG8_MMA(1, 0, At, B0); PG8_MMA(1, 1, At, B1); PG8_BAR; PG8_SCHED;
;             PG8_LDB(B0, 1, 0); PG8_LDB(B1, 1, 1); PG8_SCHED; PG8_LDA(At, 1, 0); PG8_STAGE(PG8_SA(0, 1), a2 + hstepA, voffA);
;             PG8_WAIT_V(8); PG8_WAIT_L(0); PG8_BAR; PG8_MMA(0, 0, At, B0); PG8_MMA(0, 1, At, B1); PG8_BAR; PG8_SCHED;
	s_setprio 1
	s_waitcnt lgkmcnt(0)
	v_mfma_f32_16x16x32_bf16 v[62:65], v[150:153], v[192:195], 0
	v_mfma_f32_16x16x32_bf16 v[58:61], v[168:171], v[192:195], 0
	v_mfma_f32_16x16x32_bf16 v[54:57], v[150:153], v[200:203], 0
	v_mfma_f32_16x16x32_bf16 v[46:49], v[168:171], v[200:203], 0
	v_mfma_f32_16x16x32_bf16 v[38:41], v[150:153], v[208:211], 0
	v_mfma_f32_16x16x32_bf16 v[30:33], v[168:171], v[208:211], 0
	v_mfma_f32_16x16x32_bf16 v[22:25], v[150:153], v[216:219], 0
	v_mfma_f32_16x16x32_bf16 v[14:17], v[168:171], v[216:219], 0
	v_mfma_f32_16x16x32_bf16 v[62:65], v[164:167], v[196:199], v[62:65]
	v_mfma_f32_16x16x32_bf16 v[58:61], v[172:175], v[196:199], v[58:61]
	v_mfma_f32_16x16x32_bf16 v[54:57], v[164:167], v[204:207], v[54:57]
	v_mfma_f32_16x16x32_bf16 v[46:49], v[172:175], v[204:207], v[46:49]
	v_mfma_f32_16x16x32_bf16 v[38:41], v[164:167], v[212:215], v[38:41]
	v_mfma_f32_16x16x32_bf16 v[30:33], v[172:175], v[212:215], v[30:33]
	v_mfma_f32_16x16x32_bf16 v[22:25], v[164:167], v[220:223], v[22:25]
	v_mfma_f32_16x16x32_bf16 v[14:17], v[172:175], v[220:223], v[14:17]
	s_setprio 0
	s_setprio 1
	v_mfma_f32_16x16x32_bf16 v[50:53], v[176:179], v[192:195], 0
	v_mfma_f32_16x16x32_bf16 v[42:45], v[184:187], v[192:195], 0
	v_mfma_f32_16x16x32_bf16 v[34:37], v[176:179], v[200:203], 0
	v_mfma_f32_16x16x32_bf16 v[26:29], v[184:187], v[200:203], 0
	v_mfma_f32_16x16x32_bf16 v[18:21], v[176:179], v[208:211], 0
	v_mfma_f32_16x16x32_bf16 v[10:13], v[184:187], v[208:211], 0
	v_mfma_f32_16x16x32_bf16 v[6:9], v[176:179], v[216:219], 0
	v_mfma_f32_16x16x32_bf16 v[2:5], v[184:187], v[216:219], 0
	v_mfma_f32_16x16x32_bf16 v[50:53], v[180:183], v[196:199], v[50:53]
	v_mfma_f32_16x16x32_bf16 v[42:45], v[188:191], v[196:199], v[42:45]
	v_mfma_f32_16x16x32_bf16 v[34:37], v[180:183], v[204:207], v[34:37]
	v_mfma_f32_16x16x32_bf16 v[26:29], v[188:191], v[204:207], v[26:29]
	v_mfma_f32_16x16x32_bf16 v[18:21], v[180:183], v[212:215], v[18:21]
	v_mfma_f32_16x16x32_bf16 v[10:13], v[188:191], v[212:215], v[10:13]
	v_mfma_f32_16x16x32_bf16 v[6:9], v[180:183], v[220:223], v[6:9]
	v_mfma_f32_16x16x32_bf16 v[2:5], v[188:191], v[220:223], v[2:5]
	s_setprio 0
	s_barrier
	s_add_i32 s58, 0, 0x18000
	v_add_u32_e32 v138, s58, v157
	s_add_i32 s59, 0, 0x1c000
	ds_read_b128 v[150:153], v138
	ds_read_b128 v[164:167], v138 offset:1024
	ds_read_b128 v[168:171], v138 offset:2048
	ds_read_b128 v[172:175], v138 offset:3072
	v_add_u32_e32 v138, s59, v157
	ds_read_b128 v[176:179], v138
	ds_read_b128 v[180:183], v138 offset:1024
	ds_read_b128 v[184:187], v138 offset:2048
	ds_read_b128 v[188:191], v138 offset:3072
	s_add_u32 s26, s26, 0x40000
	s_addc_u32 s27, s27, 0
	s_mov_b32 m0, s35
	v_lshl_add_u64 v[232:233], s[26:27], 0, v[136:137]
	ds_read_b128 v[192:195], v162 offset:32768
	ds_read_b128 v[196:199], v162 offset:33792
	ds_read_b128 v[200:203], v162 offset:34816
	ds_read_b128 v[204:207], v162 offset:35840
	ds_read_b128 v[208:211], v162 offset:36864
	ds_read_b128 v[212:215], v162 offset:37888
	ds_read_b128 v[216:219], v162 offset:38912
	ds_read_b128 v[220:223], v162 offset:39936
	global_load_lds_dwordx4 v[232:233], off
	v_lshl_add_u64 v[232:233], s[26:27], 0, v[132:133]
	s_mov_b32 m0, s36
	s_nop 0
	global_load_lds_dwordx4 v[232:233], off
	s_waitcnt vmcnt(8)
	s_waitcnt lgkmcnt(0)
	s_barrier
	s_setprio 1
	s_waitcnt lgkmcnt(0)
	v_mfma_f32_16x16x32_bf16 v[126:129], v[150:153], v[192:195], v[126:129]
	v_mfma_f32_16x16x32_bf16 v[122:125], v[168:171], v[192:195], v[122:125]
	v_mfma_f32_16x16x32_bf16 v[114:117], v[150:153], v[200:203], v[114:117]
	v_mfma_f32_16x16x32_bf16 v[106:109], v[168:171], v[200:203], v[106:109]
	v_mfma_f32_16x16x32_bf16 v[102:105], v[150:153], v[208:211], v[102:105]
	v_mfma_f32_16x16x32_bf16 v[94:97], v[168:171], v[208:211], v[94:97]
	v_mfma_f32_16x16x32_bf16 v[86:89], v[150:153], v[216:219], v[86:89]
	v_mfma_f32_16x16x32_bf16 v[78:81], v[168:171], v[216:219], v[78:81]
	v_mfma_f32_16x16x32_bf16 v[126:129], v[164:167], v[196:199], v[126:129]
	v_mfma_f32_16x16x32_bf16 v[122:125], v[172:175], v[196:199], v[122:125]
	v_mfma_f32_16x16x32_bf16 v[114:117], v[164:167], v[204:207], v[114:117]
	v_mfma_f32_16x16x32_bf16 v[106:109], v[172:175], v[204:207], v[106:109]
	v_mfma_f32_16x16x32_bf16 v[102:105], v[164:167], v[212:215], v[102:105]
	v_mfma_f32_16x16x32_bf16 v[94:97], v[172:175], v[212:215], v[94:97]
	v_mfma_f32_16x16x32_bf16 v[86:89], v[164:167], v[220:223], v[86:89]
	v_mfma_f32_16x16x32_bf16 v[78:81], v[172:175], v[220:223], v[78:81]
	s_setprio 0
	s_setprio 1
	v_mfma_f32_16x16x32_bf16 v[118:121], v[176:179], v[192:195], v[118:121]
	v_mfma_f32_16x16x32_bf16 v[110:113], v[184:187], v[192:195], v[110:113]
	v_mfma_f32_16x16x32_bf16 v[98:101], v[176:179], v[200:203], v[98:101]
	v_mfma_f32_16x16x32_bf16 v[90:93], v[184:187], v[200:203], v[90:93]
	v_mfma_f32_16x16x32_bf16 v[82:85], v[176:179], v[208:211], v[82:85]
	v_mfma_f32_16x16x32_bf16 v[74:77], v[184:187], v[208:211], v[74:77]
	v_mfma_f32_16x16x32_bf16 v[70:73], v[176:179], v[216:219], v[70:73]
	v_mfma_f32_16x16x32_bf16 v[66:69], v[184:187], v[216:219], v[66:69]
	v_mfma_f32_16x16x32_bf16 v[118:121], v[180:183], v[196:199], v[118:121]
	v_mfma_f32_16x16x32_bf16 v[110:113], v[188:191], v[196:199], v[110:113]
	v_mfma_f32_16x16x32_bf16 v[98:101], v[180:183], v[204:207], v[98:101]
	v_mfma_f32_16x16x32_bf16 v[90:93], v[188:191], v[204:207], v[90:93]
	v_mfma_f32_16x16x32_bf16 v[82:85], v[180:183], v[212:215], v[82:85]
	v_mfma_f32_16x16x32_bf16 v[74:77], v[188:191], v[212:215], v[74:77]
	v_mfma_f32_16x16x32_bf16 v[70:73], v[180:183], v[220:223], v[70:73]
	v_mfma_f32_16x16x32_bf16 v[66:69], v[188:191], v[220:223], v[66:69]
	s_setprio 0
	s_barrier
; #define PG8_STAGE(bufoff, gbase, voff) do { _Pragma("unroll") for (int _i = 0; _i < 2; ++_i) \
;         __builtin_amdgcn_global_load_lds((const unsigned*)((const char*)(gbase) + (voff)[_i]), (PG8_LAS unsigned*)(lds + (bufoff) + ldsw + _i * 8192), 16, 0, 0); } while (0)
; #define PG8_LDA(dst, b, h) do { _Pragma("unroll") for (int m = 0; m < 4; ++m) _Pragma("unroll") for (int k = 0; k < 2; ++k) dst[m][k] = *(const PG8_LAS bf16x8*)(lds + PG8_SA(b, h) + aoff + m * 2048 + k * 1024); } while (0)
; #define PG8_MMA(ai, bj, At, Bt) do { __builtin_amdgcn_s_setprio(1); _Pragma("unroll") for (int m = 0; m < 4; ++m) _Pragma("unroll") for (int n = 0; n < 2; ++n) _Pragma("unroll") for (int k = 0; k < 2; ++k) \
;         acc[ai][bj][m][n] = __builtin_amdgcn_mfma_f32_16x16x32_bf16(Bt[n][k], At[m][k], acc[ai][bj][m][n], 0, 0, 0); __builtin_amdgcn_s_setprio(0); } while (0)
; #define PG8_WAIT_V(n) asm volatile("s_waitcnt vmcnt(" #n ")" ::: "memory")
; #define PG8_WAIT_L(n) asm volatile("s_waitcnt lgkmcnt(" #n ")" ::: "memory")
; #define PG8_BAR __builtin_amdgcn_s_barrier()
; #define PG8_SCHED __builtin_amdgcn_sched_barrier(0)
; template <class Epi, class Sched, bool ALIGN_EPI = false, bool SP2 = false, bool AGM = false  >
; __device__ __forceinline__ void gemm_phase(PG8_LAS unsigned char* lds, const Gemm g, const Sched& S, const Epi& E) {
;     ...
;         for (int t = 0; t < nt; t += 2) {
;             const bool last = (t == nt - 2);
;     ...
;             PG8_LDA(At, 1, 1); PG8_STAGE(PG8_SB(1, 0), b3, voffB); PG8_STAGE(PG8_SB(1, 1), b3 + hstep, voffB); PG8_STAGE(PG8_SA(1, 0), a3, voffA);
;             PG8_WAIT_V(8); PG8_WAIT_L(0); PG8_BAR; PG8_MMA(1, 0, At, B0); PG8_MMA(1, 1, At, B1); PG8_BAR; PG8_SCHED;
	s_add_i32 s26, s58, s29
	v_lshl_add_u64 v[224:225], v[224:225], 0, s[10:11]
	s_mov_b32 m0, s26
	ds_read_b128 v[192:195], v162 offset:49152
	ds_read_b128 v[196:199], v162 offset:50176
	ds_read_b128 v[200:203], v162 offset:51200
	ds_read_b128 v[204:207], v162 offset:52224
	ds_read_b128 v[208:211], v162 offset:53248
	ds_read_b128 v[212:215], v162 offset:54272
	ds_read_b128 v[216:219], v162 offset:55296
	ds_read_b128 v[220:223], v162 offset:56320
	global_load_lds_dwordx4 v[224:225], off
	s_add_i32 m0, s26, 0x2000
	s_add_u32 s24, s24, 0x40080
	v_lshl_add_u64 v[224:225], v[226:227], 0, s[10:11]
	s_addc_u32 s25, s25, 0
	s_add_i32 s26, s59, s29
	global_load_lds_dwordx4 v[224:225], off
	v_lshl_add_u64 v[224:225], s[24:25], 0, v[134:135]
	s_mov_b32 m0, s26
	s_nop 0
	global_load_lds_dwordx4 v[224:225], off
	v_lshl_add_u64 v[224:225], s[24:25], 0, v[130:131]
	s_add_i32 m0, s26, 0x2000
	s_nop 0
	global_load_lds_dwordx4 v[224:225], off
	v_lshl_add_u64 v[224:225], v[228:229], 0, s[10:11]
	s_mov_b32 m0, s38
	s_nop 0
	global_load_lds_dwordx4 v[224:225], off
	v_lshl_add_u64 v[224:225], v[230:231], 0, s[10:11]
	s_mov_b32 m0, s39
	s_nop 0
	global_load_lds_dwordx4 v[224:225], off
	s_waitcnt vmcnt(8)
	s_waitcnt lgkmcnt(0)
	s_barrier
	s_setprio 1
	s_waitcnt lgkmcnt(0)
	v_mfma_f32_16x16x32_bf16 v[62:65], v[150:153], v[192:195], v[62:65]
	v_mfma_f32_16x16x32_bf16 v[58:61], v[168:171], v[192:195], v[58:61]
	v_mfma_f32_16x16x32_bf16 v[54:57], v[150:153], v[200:203], v[54:57]
	v_mfma_f32_16x16x32_bf16 v[46:49], v[168:171], v[200:203], v[46:49]
	v_mfma_f32_16x16x32_bf16 v[38:41], v[150:153], v[208:211], v[38:41]
	v_mfma_f32_16x16x32_bf16 v[30:33], v[168:171], v[208:211], v[30:33]
	v_mfma_f32_16x16x32_bf16 v[22:25], v[150:153], v[216:219], v[22:25]
	v_mfma_f32_16x16x32_bf16 v[14:17], v[168:171], v[216:219], v[14:17]
	v_mfma_f32_16x16x32_bf16 v[62:65], v[164:167], v[196:199], v[62:65]
	v_mfma_f32_16x16x32_bf16 v[58:61], v[172:175], v[196:199], v[58:61]
	v_mfma_f32_16x16x32_bf16 v[54:57], v[164:167], v[204:207], v[54:57]
	v_mfma_f32_16x16x32_bf16 v[46:49], v[172:175], v[204:207], v[46:49]
	v_mfma_f32_16x16x32_bf16 v[38:41], v[164:167], v[212:215], v[38:41]
	v_mfma_f32_16x16x32_bf16 v[30:33], v[172:175], v[212:215], v[30:33]
	v_mfma_f32_16x16x32_bf16 v[22:25], v[164:167], v[220:223], v[22:25]
	v_mfma_f32_16x16x32_bf16 v[14:17], v[172:175], v[220:223], v[14:17]
	s_setprio 0
	s_setprio 1
	v_mfma_f32_16x16x32_bf16 v[50:53], v[176:179], v[192:195], v[50:53]
	v_mfma_f32_16x16x32_bf16 v[42:45], v[184:187], v[192:195], v[42:45]
	v_mfma_f32_16x16x32_bf16 v[34:37], v[176:179], v[200:203], v[34:37]
	v_mfma_f32_16x16x32_bf16 v[26:29], v[184:187], v[200:203], v[26:29]
	v_mfma_f32_16x16x32_bf16 v[18:21], v[176:179], v[208:211], v[18:21]
	v_mfma_f32_16x16x32_bf16 v[10:13], v[184:187], v[208:211], v[10:13]
	v_mfma_f32_16x16x32_bf16 v[6:9], v[176:179], v[216:219], v[6:9]
	v_mfma_f32_16x16x32_bf16 v[2:5], v[184:187], v[216:219], v[2:5]
	v_mfma_f32_16x16x32_bf16 v[50:53], v[180:183], v[196:199], v[50:53]
	v_mfma_f32_16x16x32_bf16 v[42:45], v[188:191], v[196:199], v[42:45]
	v_mfma_f32_16x16x32_bf16 v[34:37], v[180:183], v[204:207], v[34:37]
	v_mfma_f32_16x16x32_bf16 v[26:29], v[188:191], v[204:207], v[26:29]
	v_mfma_f32_16x16x32_bf16 v[18:21], v[180:183], v[212:215], v[18:21]
	v_mfma_f32_16x16x32_bf16 v[10:13], v[188:191], v[212:215], v[10:13]
	v_mfma_f32_16x16x32_bf16 v[6:9], v[180:183], v[220:223], v[6:9]
	v_mfma_f32_16x16x32_bf16 v[2:5], v[188:191], v[220:223], v[2:5]
	s_setprio 0
	s_barrier
	s_add_i32 s55, s55, 2
	s_add_u32 s22, s22, 0x100
	s_addc_u32 s23, s23, 0
	s_add_u32 s53, s53, 0x100
	s_addc_u32 s54, s54, 0
	s_cmp_gt_u32 s55, 13
	s_cbranch_scc1 .Lpeel_done_p1

; #define PG8_BAR __builtin_amdgcn_s_barrier()
; template <class Epi, class Sched, bool ALIGN_EPI = false, bool SP2 = false, bool AGM = false  >
; __device__ __forceinline__ void gemm_phase(PG8_LAS unsigned char* lds, const Gemm g, const Sched& S, const Epi& E) {
;     ...
;         if constexpr (ALIGN_EPI) { if (wr == 0) PG8_BAR; }
;         if constexpr (!Epi::AFTER_DRAIN) { E(acc, cur, wr, wc, fr, fq); S.done(cur); }
;         if (!has_next) break;
.Lpeel_done_p1:
	s_and_b64 vcc, exec, s[4:5]
	s_cbranch_vccz .LBB0_140
	s_barrier

; #define PG8_STAGE(bufoff, gbase, voff) do { _Pragma("unroll") for (int _i = 0; _i < 2; ++_i) \
;         __builtin_amdgcn_global_load_lds((const unsigned*)((const char*)(gbase) + (voff)[_i]), (PG8_LAS unsigned*)(lds + (bufoff) + ldsw + _i * 8192), 16, 0, 0); } while (0)
; #define PG8_LDA(dst, b, h) do { _Pragma("unroll") for (int m = 0; m < 4; ++m) _Pragma("unroll") for (int k = 0; k < 2; ++k) dst[m][k] = *(const PG8_LAS bf16x8*)(lds + PG8_SA(b, h) + aoff + m * 2048 + k * 1024); } while (0)
; #define PG8_LDB(dst, b, h) do { _Pragma("unroll") for (int n = 0; n < 2; ++n) _Pragma("unroll") for (int k = 0; k < 2; ++k) dst[n][k] = *(const PG8_LAS bf16x8*)(lds + PG8_SB(b, h) + boff + n * 2048 + k * 1024); } while (0)
; #define PG8_MMA(ai, bj, At, Bt) do { __builtin_amdgcn_s_setprio(1); _Pragma("unroll") for (int m = 0; m < 4; ++m) _Pragma("unroll") for (int n = 0; n < 2; ++n) _Pragma("unroll") for (int k = 0; k < 2; ++k) \
;         acc[ai][bj][m][n] = __builtin_amdgcn_mfma_f32_16x16x32_bf16(Bt[n][k], At[m][k], acc[ai][bj][m][n], 0, 0, 0); __builtin_amdgcn_s_setprio(0); } while (0)
; #define PG8_WAIT_V(n) asm volatile("s_waitcnt vmcnt(" #n ")" ::: "memory")
; #define PG8_WAIT_L(n) asm volatile("s_waitcnt lgkmcnt(" #n ")" ::: "memory")
; #define PG8_BAR __builtin_amdgcn_s_barrier()
; #define PG8_SCHED __builtin_amdgcn_sched_barrier(0)
; template <class Epi, class Sched, bool ALIGN_EPI = false, bool SP2 = false, bool AGM = false  >
; __device__ __forceinline__ void gemm_phase(PG8_LAS unsigned char* lds, const Gemm g, const Sched& S, const Epi& E) {
;     ...
;             PG8_LDB(B0, 0, 0); PG8_LDB(B1, 0, 1); PG8_SCHED; PG8_LDA(At, 0, 0); PG8_STAGE(PG8_SA(1, 1), a1 + hstepA, voffA);
;             PG8_WAIT_V(8); PG8_WAIT_L(0); PG8_BAR; PG8_MMA(0, 0, At, B0); PG8_MMA(0, 1, At, B1); PG8_BAR; PG8_SCHED;
;             PG8_LDA(At, 0, 1); PG8_STAGE(PG8_SB(0, 0), b2, voffB); PG8_STAGE(PG8_SB(0, 1), b2 + hstep, voffB); PG8_STAGE(PG8_SA(0, 0), a2, voffA);
;             PG8_WAIT_V(8); PG8_WAIT_L(0); PG8_BAR; PG8_MMA(1, 0, At, B0); PG8_MMA(1, 1, At, B1); PG8_BAR; PG8_SCHED;
;     ...
; #pragma unroll
;         for (int a = 0; a < 2; ++a)
; #pragma unroll
;             for (int b = 0; b < 2; ++b)
; #pragma unroll
;                 for (int m = 0; m < 4; ++m)
; #pragma unroll
;                     for (int n = 0; n < 2; ++n) acc[a][b][m][n] = (f32x4){0.f, 0.f, 0.f, 0.f};
.LBB0_876:
	s_ashr_i32 s23, s22, 31
	s_lshl_b64 s[24:25], s[22:23], 19
	s_add_u32 s24, s46, s24
	s_addc_u32 s25, s47, s25
	s_and_b64 s[26:27], s[0:1], exec
	s_cselect_b32 s23, s25, s29
	s_cselect_b32 s64, s24, s28
	s_ashr_i32 s21, s20, 31
	s_lshl_b64 s[26:27], s[20:21], 19
	s_add_u32 s26, s10, s26
	s_addc_u32 s27, s11, s27
	s_and_b64 s[34:35], s[0:1], exec
	s_cselect_b32 s21, s27, s31
	s_cselect_b32 s65, s26, s30
	s_add_u32 s28, s28, 0x40080
	s_addc_u32 s29, s29, 0
	s_add_u32 s66, s30, 0x100
	s_addc_u32 s67, s31, 0
	s_mov_b32 s68, -2
	s_waitcnt vmcnt(0)
	s_waitcnt lgkmcnt(0)
	ds_read_b128 v[148:151], v156
	ds_read_b128 v[164:167], v156 offset:1024
	ds_read_b128 v[168:171], v156 offset:2048
	ds_read_b128 v[172:175], v156 offset:3072
	ds_read_b128 v[176:179], v157
	ds_read_b128 v[180:183], v157 offset:1024
	ds_read_b128 v[184:187], v157 offset:2048
	ds_read_b128 v[188:191], v157 offset:3072
	s_add_u32 s30, s28, 0xfffc0080
	s_addc_u32 s31, s29, -1
	s_cmp_eq_u32 s68, 12
	s_cselect_b32 s35, s23, s31
	s_cselect_b32 s34, s64, s30
	s_cselect_b32 s31, s21, s67
	s_cselect_b32 s30, s65, s66
	v_lshl_add_u64 v[224:225], s[28:29], 0, v[140:141]
	s_add_i32 m0, s37, 0xc000
	ds_read_b128 v[192:195], v158
	ds_read_b128 v[196:199], v158 offset:1024
	ds_read_b128 v[200:203], v158 offset:2048
	ds_read_b128 v[204:207], v158 offset:3072
	ds_read_b128 v[208:211], v158 offset:4096
	ds_read_b128 v[212:215], v158 offset:5120
	ds_read_b128 v[216:219], v158 offset:6144
	ds_read_b128 v[220:223], v158 offset:7168
	global_load_lds_dwordx4 v[224:225], off
	v_lshl_add_u64 v[224:225], s[28:29], 0, v[142:143]
	s_add_i32 m0, s37, 0xe000
	s_nop 0
	global_load_lds_dwordx4 v[224:225], off
	s_waitcnt vmcnt(8)
	s_waitcnt lgkmcnt(0)
	s_barrier
	s_setprio 1
	s_waitcnt lgkmcnt(0)
	v_mfma_f32_16x16x32_bf16 v[126:129], v[148:151], v[192:195], 0
	v_mfma_f32_16x16x32_bf16 v[122:125], v[168:171], v[192:195], 0
	v_mfma_f32_16x16x32_bf16 v[110:113], v[148:151], v[200:203], 0
	v_mfma_f32_16x16x32_bf16 v[106:109], v[168:171], v[200:203], 0
	v_mfma_f32_16x16x32_bf16 v[94:97], v[148:151], v[208:211], 0
	v_mfma_f32_16x16x32_bf16 v[90:93], v[168:171], v[208:211], 0
	v_mfma_f32_16x16x32_bf16 v[78:81], v[148:151], v[216:219], 0
	v_mfma_f32_16x16x32_bf16 v[74:77], v[168:171], v[216:219], 0
	v_mfma_f32_16x16x32_bf16 v[126:129], v[164:167], v[196:199], v[126:129]
	v_mfma_f32_16x16x32_bf16 v[122:125], v[172:175], v[196:199], v[122:125]
	v_mfma_f32_16x16x32_bf16 v[110:113], v[164:167], v[204:207], v[110:113]
	v_mfma_f32_16x16x32_bf16 v[106:109], v[172:175], v[204:207], v[106:109]
	v_mfma_f32_16x16x32_bf16 v[94:97], v[164:167], v[212:215], v[94:97]
	v_mfma_f32_16x16x32_bf16 v[90:93], v[172:175], v[212:215], v[90:93]
	v_mfma_f32_16x16x32_bf16 v[78:81], v[164:167], v[220:223], v[78:81]
	v_mfma_f32_16x16x32_bf16 v[74:77], v[172:175], v[220:223], v[74:77]
	s_setprio 0
	s_setprio 1
	v_mfma_f32_16x16x32_bf16 v[118:121], v[176:179], v[192:195], 0
	v_mfma_f32_16x16x32_bf16 v[114:117], v[184:187], v[192:195], 0
	v_mfma_f32_16x16x32_bf16 v[102:105], v[176:179], v[200:203], 0
	v_mfma_f32_16x16x32_bf16 v[98:101], v[184:187], v[200:203], 0
	v_mfma_f32_16x16x32_bf16 v[86:89], v[176:179], v[208:211], 0
	v_mfma_f32_16x16x32_bf16 v[82:85], v[184:187], v[208:211], 0
	v_mfma_f32_16x16x32_bf16 v[70:73], v[176:179], v[216:219], 0
	v_mfma_f32_16x16x32_bf16 v[66:69], v[184:187], v[216:219], 0
	v_mfma_f32_16x16x32_bf16 v[118:121], v[180:183], v[196:199], v[118:121]
	v_mfma_f32_16x16x32_bf16 v[114:117], v[188:191], v[196:199], v[114:117]
	v_mfma_f32_16x16x32_bf16 v[102:105], v[180:183], v[204:207], v[102:105]
	v_mfma_f32_16x16x32_bf16 v[98:101], v[188:191], v[204:207], v[98:101]
	v_mfma_f32_16x16x32_bf16 v[86:89], v[180:183], v[212:215], v[86:89]
	v_mfma_f32_16x16x32_bf16 v[82:85], v[188:191], v[212:215], v[82:85]
	v_mfma_f32_16x16x32_bf16 v[70:73], v[180:183], v[220:223], v[70:73]
	v_mfma_f32_16x16x32_bf16 v[66:69], v[188:191], v[220:223], v[66:69]
	s_setprio 0
	s_barrier
	s_add_i32 s69, s53, s3
	v_lshl_add_u64 v[224:225], s[30:31], 0, v[134:135]
	s_mov_b32 m0, s69
	ds_read_b128 v[192:195], v158 offset:16384
	ds_read_b128 v[196:199], v158 offset:17408
	ds_read_b128 v[200:203], v158 offset:18432
	ds_read_b128 v[204:207], v158 offset:19456
	ds_read_b128 v[208:211], v158 offset:20480
	ds_read_b128 v[212:215], v158 offset:21504
	ds_read_b128 v[216:219], v158 offset:22528
	ds_read_b128 v[220:223], v158 offset:23552
	global_load_lds_dwordx4 v[224:225], off
	s_add_i32 m0, s69, 0x2000
	s_add_u32 s70, s30, 0x40000
	v_lshl_add_u64 v[226:227], s[30:31], 0, v[130:131]
	s_addc_u32 s71, s31, 0
	s_add_i32 s69, s54, s3
	global_load_lds_dwordx4 v[226:227], off
	v_lshl_add_u64 v[228:229], s[70:71], 0, v[134:135]
	s_mov_b32 m0, s69
	v_lshl_add_u64 v[230:231], s[34:35], 0, v[132:133]
	global_load_lds_dwordx4 v[228:229], off
	v_lshl_add_u64 v[228:229], s[70:71], 0, v[130:131]
	s_add_i32 m0, s69, 0x2000
	s_nop 0
	global_load_lds_dwordx4 v[228:229], off
	v_lshl_add_u64 v[228:229], s[34:35], 0, v[136:137]
	s_mov_b32 m0, s37
	s_nop 0
	global_load_lds_dwordx4 v[228:229], off
	s_mov_b32 m0, s38
	s_nop 0
	global_load_lds_dwordx4 v[230:231], off
	s_waitcnt vmcnt(8)
	s_waitcnt lgkmcnt(0)
	s_barrier
; #define PG8_STAGE(bufoff, gbase, voff) do { _Pragma("unroll") for (int _i = 0; _i < 2; ++_i) \
;         __builtin_amdgcn_global_load_lds((const unsigned*)((const char*)(gbase) + (voff)[_i]), (PG8_LAS unsigned*)(lds + (bufoff) + ldsw + _i * 8192), 16, 0, 0); } while (0)
; #define PG8_LDA(dst, b, h) do { _Pragma("unroll") for (int m = 0; m < 4; ++m) _Pragma("unroll") for (int k = 0; k < 2; ++k) dst[m][k] = *(const PG8_LAS bf16x8*)(lds + PG8_SA(b, h) + aoff + m * 2048 + k * 1024); } while (0)
; #define PG8_LDB(dst, b, h) do { _Pragma("unroll") for (int n = 0; n < 2; ++n) _Pragma("unroll") for (int k = 0; k < 2; ++k) dst[n][k] = *(const PG8_LAS bf16x8*)(lds + PG8_SB(b, h) + boff + n * 2048 + k * 1024); } while (0)
; #define PG8_MMA(ai, bj, At, Bt) do { __builtin_amdgcn_s_setprio(1); _Pragma("unroll") for (int m = 0; m < 4; ++m) _Pragma("unroll") for (int n = 0; n < 2; ++n) _Pragma("unroll") for (int k = 0; k < 2; ++k) \
;         acc[ai][bj][m][n] = __builtin_amdgcn_mfma_f32_16x16x32_bf16(Bt[n][k], At[m][k], acc[ai][bj][m][n], 0, 0, 0); __builtin_amdgcn_s_setprio(0); } while (0)
; #define PG8_WAIT_V(n) asm volatile("s_waitcnt vmcnt(" #n ")" ::: "memory")
; #define PG8_WAIT_L(n) asm volatile("s_waitcnt lgkmcnt(" #n ")" ::: "memory")
; #define PG8_BAR __builtin_amdgcn_s_barrier()
; #define PG8_SCHED __builtin_amdgcn_sched_barrier(0)
; template <class Epi, class Sched, bool ALIGN_EPI = false, bool SP2 = false, bool AGM = false  >
; __device__ __forceinline__ void gemm_phase(PG8_LAS unsigned char* lds, const Gemm g, const Sched& S, const Epi& E) {
;     ...
;             PG8_WAIT_V(8); PG8_WAIT_L(0); PG8_BAR; PG8_MMA(1, 0, At, B0); PG8_MMA(1, 1, At, B1); PG8_BAR; PG8_SCHED;
;             PG8_LDB(B0, 1, 0); PG8_LDB(B1, 1, 1); PG8_SCHED; PG8_LDA(At, 1, 0); PG8_STAGE(PG8_SA(0, 1), a2 + hstepA, voffA);
;             PG8_WAIT_V(8); PG8_WAIT_L(0); PG8_BAR; PG8_MMA(0, 0, At, B0); PG8_MMA(0, 1, At, B1); PG8_BAR; PG8_SCHED;
	s_setprio 1
	s_waitcnt lgkmcnt(0)
	v_mfma_f32_16x16x32_bf16 v[62:65], v[148:151], v[192:195], 0
	v_mfma_f32_16x16x32_bf16 v[58:61], v[168:171], v[192:195], 0
	v_mfma_f32_16x16x32_bf16 v[46:49], v[148:151], v[200:203], 0
	v_mfma_f32_16x16x32_bf16 v[42:45], v[168:171], v[200:203], 0
	v_mfma_f32_16x16x32_bf16 v[30:33], v[148:151], v[208:211], 0
	v_mfma_f32_16x16x32_bf16 v[26:29], v[168:171], v[208:211], 0
	v_mfma_f32_16x16x32_bf16 v[14:17], v[148:151], v[216:219], 0
	v_mfma_f32_16x16x32_bf16 v[10:13], v[168:171], v[216:219], 0
	v_mfma_f32_16x16x32_bf16 v[62:65], v[164:167], v[196:199], v[62:65]
	v_mfma_f32_16x16x32_bf16 v[58:61], v[172:175], v[196:199], v[58:61]
	v_mfma_f32_16x16x32_bf16 v[46:49], v[164:167], v[204:207], v[46:49]
	v_mfma_f32_16x16x32_bf16 v[42:45], v[172:175], v[204:207], v[42:45]
	v_mfma_f32_16x16x32_bf16 v[30:33], v[164:167], v[212:215], v[30:33]
	v_mfma_f32_16x16x32_bf16 v[26:29], v[172:175], v[212:215], v[26:29]
	v_mfma_f32_16x16x32_bf16 v[14:17], v[164:167], v[220:223], v[14:17]
	v_mfma_f32_16x16x32_bf16 v[10:13], v[172:175], v[220:223], v[10:13]
	s_setprio 0
	s_setprio 1
	v_mfma_f32_16x16x32_bf16 v[54:57], v[176:179], v[192:195], 0
	v_mfma_f32_16x16x32_bf16 v[50:53], v[184:187], v[192:195], 0
	v_mfma_f32_16x16x32_bf16 v[38:41], v[176:179], v[200:203], 0
	v_mfma_f32_16x16x32_bf16 v[34:37], v[184:187], v[200:203], 0
	v_mfma_f32_16x16x32_bf16 v[22:25], v[176:179], v[208:211], 0
	v_mfma_f32_16x16x32_bf16 v[18:21], v[184:187], v[208:211], 0
	v_mfma_f32_16x16x32_bf16 v[6:9], v[176:179], v[216:219], 0
	v_mfma_f32_16x16x32_bf16 v[2:5], v[184:187], v[216:219], 0
	v_mfma_f32_16x16x32_bf16 v[54:57], v[180:183], v[196:199], v[54:57]
	v_mfma_f32_16x16x32_bf16 v[50:53], v[188:191], v[196:199], v[50:53]
	v_mfma_f32_16x16x32_bf16 v[38:41], v[180:183], v[204:207], v[38:41]
	v_mfma_f32_16x16x32_bf16 v[34:37], v[188:191], v[204:207], v[34:37]
	v_mfma_f32_16x16x32_bf16 v[22:25], v[180:183], v[212:215], v[22:25]
	v_mfma_f32_16x16x32_bf16 v[18:21], v[188:191], v[212:215], v[18:21]
	v_mfma_f32_16x16x32_bf16 v[6:9], v[180:183], v[220:223], v[6:9]
	v_mfma_f32_16x16x32_bf16 v[2:5], v[188:191], v[220:223], v[2:5]
	s_setprio 0
	s_barrier
	s_add_i32 s69, 0, 0x18000
	s_add_i32 s70, 0, 0x1c000
	v_add_u32_e32 v172, s69, v155
	v_add_u32_e32 v188, s70, v155
	ds_read_b128 v[148:151], v172
	ds_read_b128 v[164:167], v172 offset:1024
	ds_read_b128 v[168:171], v172 offset:2048
	ds_read_b128 v[172:175], v172 offset:3072
	ds_read_b128 v[176:179], v188
	ds_read_b128 v[180:183], v188 offset:1024
	ds_read_b128 v[184:187], v188 offset:2048
	ds_read_b128 v[188:191], v188 offset:3072
	s_add_u32 s34, s34, 0x40000
	s_addc_u32 s35, s35, 0
	s_mov_b32 m0, s39
	v_lshl_add_u64 v[232:233], s[34:35], 0, v[136:137]
	ds_read_b128 v[192:195], v158 offset:32768
	ds_read_b128 v[196:199], v158 offset:33792
	ds_read_b128 v[200:203], v158 offset:34816
	ds_read_b128 v[204:207], v158 offset:35840
	ds_read_b128 v[208:211], v158 offset:36864
	ds_read_b128 v[212:215], v158 offset:37888
	ds_read_b128 v[216:219], v158 offset:38912
	ds_read_b128 v[220:223], v158 offset:39936
	global_load_lds_dwordx4 v[232:233], off
	v_lshl_add_u64 v[232:233], s[34:35], 0, v[132:133]
	s_mov_b32 m0, s40
	s_nop 0
	global_load_lds_dwordx4 v[232:233], off
	s_waitcnt vmcnt(8)
	s_waitcnt lgkmcnt(0)
	s_barrier
	s_setprio 1
	s_waitcnt lgkmcnt(0)
	v_mfma_f32_16x16x32_bf16 v[126:129], v[148:151], v[192:195], v[126:129]
	v_mfma_f32_16x16x32_bf16 v[122:125], v[168:171], v[192:195], v[122:125]
	v_mfma_f32_16x16x32_bf16 v[110:113], v[148:151], v[200:203], v[110:113]
	v_mfma_f32_16x16x32_bf16 v[106:109], v[168:171], v[200:203], v[106:109]
	v_mfma_f32_16x16x32_bf16 v[94:97], v[148:151], v[208:211], v[94:97]
	v_mfma_f32_16x16x32_bf16 v[90:93], v[168:171], v[208:211], v[90:93]
	v_mfma_f32_16x16x32_bf16 v[78:81], v[148:151], v[216:219], v[78:81]
	v_mfma_f32_16x16x32_bf16 v[74:77], v[168:171], v[216:219], v[74:77]
	v_mfma_f32_16x16x32_bf16 v[126:129], v[164:167], v[196:199], v[126:129]
	v_mfma_f32_16x16x32_bf16 v[122:125], v[172:175], v[196:199], v[122:125]
	v_mfma_f32_16x16x32_bf16 v[110:113], v[164:167], v[204:207], v[110:113]
	v_mfma_f32_16x16x32_bf16 v[106:109], v[172:175], v[204:207], v[106:109]
	v_mfma_f32_16x16x32_bf16 v[94:97], v[164:167], v[212:215], v[94:97]
	v_mfma_f32_16x16x32_bf16 v[90:93], v[172:175], v[212:215], v[90:93]
	v_mfma_f32_16x16x32_bf16 v[78:81], v[164:167], v[220:223], v[78:81]
	v_mfma_f32_16x16x32_bf16 v[74:77], v[172:175], v[220:223], v[74:77]
	s_setprio 0
	s_setprio 1
	v_mfma_f32_16x16x32_bf16 v[118:121], v[176:179], v[192:195], v[118:121]
	v_mfma_f32_16x16x32_bf16 v[114:117], v[184:187], v[192:195], v[114:117]
	v_mfma_f32_16x16x32_bf16 v[102:105], v[176:179], v[200:203], v[102:105]
	v_mfma_f32_16x16x32_bf16 v[98:101], v[184:187], v[200:203], v[98:101]
	v_mfma_f32_16x16x32_bf16 v[86:89], v[176:179], v[208:211], v[86:89]
	v_mfma_f32_16x16x32_bf16 v[82:85], v[184:187], v[208:211], v[82:85]
	v_mfma_f32_16x16x32_bf16 v[70:73], v[176:179], v[216:219], v[70:73]
	v_mfma_f32_16x16x32_bf16 v[66:69], v[184:187], v[216:219], v[66:69]
	v_mfma_f32_16x16x32_bf16 v[118:121], v[180:183], v[196:199], v[118:121]
	v_mfma_f32_16x16x32_bf16 v[114:117], v[188:191], v[196:199], v[114:117]
	v_mfma_f32_16x16x32_bf16 v[102:105], v[180:183], v[204:207], v[102:105]
	v_mfma_f32_16x16x32_bf16 v[98:101], v[188:191], v[204:207], v[98:101]
	v_mfma_f32_16x16x32_bf16 v[86:89], v[180:183], v[212:215], v[86:89]
	v_mfma_f32_16x16x32_bf16 v[82:85], v[188:191], v[212:215], v[82:85]
	v_mfma_f32_16x16x32_bf16 v[70:73], v[180:183], v[220:223], v[70:73]
	v_mfma_f32_16x16x32_bf16 v[66:69], v[188:191], v[220:223], v[66:69]
	s_setprio 0
	s_barrier
; #define PG8_STAGE(bufoff, gbase, voff) do { _Pragma("unroll") for (int _i = 0; _i < 2; ++_i) \
;         __builtin_amdgcn_global_load_lds((const unsigned*)((const char*)(gbase) + (voff)[_i]), (PG8_LAS unsigned*)(lds + (bufoff) + ldsw + _i * 8192), 16, 0, 0); } while (0)
; #define PG8_LDA(dst, b, h) do { _Pragma("unroll") for (int m = 0; m < 4; ++m) _Pragma("unroll") for (int k = 0; k < 2; ++k) dst[m][k] = *(const PG8_LAS bf16x8*)(lds + PG8_SA(b, h) + aoff + m * 2048 + k * 1024); } while (0)
; #define PG8_MMA(ai, bj, At, Bt) do { __builtin_amdgcn_s_setprio(1); _Pragma("unroll") for (int m = 0; m < 4; ++m) _Pragma("unroll") for (int n = 0; n < 2; ++n) _Pragma("unroll") for (int k = 0; k < 2; ++k) \
;         acc[ai][bj][m][n] = __builtin_amdgcn_mfma_f32_16x16x32_bf16(Bt[n][k], At[m][k], acc[ai][bj][m][n], 0, 0, 0); __builtin_amdgcn_s_setprio(0); } while (0)
; #define PG8_WAIT_V(n) asm volatile("s_waitcnt vmcnt(" #n ")" ::: "memory")
; #define PG8_WAIT_L(n) asm volatile("s_waitcnt lgkmcnt(" #n ")" ::: "memory")
; #define PG8_BAR __builtin_amdgcn_s_barrier()
; #define PG8_SCHED __builtin_amdgcn_sched_barrier(0)
; template <class Epi, class Sched, bool ALIGN_EPI = false, bool SP2 = false, bool AGM = false  >
; __device__ __forceinline__ void gemm_phase(PG8_LAS unsigned char* lds, const Gemm g, const Sched& S, const Epi& E) {
;     ...
;         for (int t = 0; t < nt; t += 2) {
;             const bool last = (t == nt - 2);
;     ...
;             PG8_LDA(At, 1, 1); PG8_STAGE(PG8_SB(1, 0), b3, voffB); PG8_STAGE(PG8_SB(1, 1), b3 + hstep, voffB); PG8_STAGE(PG8_SA(1, 0), a3, voffA);
;             PG8_WAIT_V(8); PG8_WAIT_L(0); PG8_BAR; PG8_MMA(1, 0, At, B0); PG8_MMA(1, 1, At, B1); PG8_BAR; PG8_SCHED;
	s_add_i32 s34, s69, s3
	v_lshl_add_u64 v[224:225], v[224:225], 0, s[16:17]
	s_mov_b32 m0, s34
	ds_read_b128 v[192:195], v158 offset:49152
	ds_read_b128 v[196:199], v158 offset:50176
	ds_read_b128 v[200:203], v158 offset:51200
	ds_read_b128 v[204:207], v158 offset:52224
	ds_read_b128 v[208:211], v158 offset:53248
	ds_read_b128 v[212:215], v158 offset:54272
	ds_read_b128 v[216:219], v158 offset:55296
	ds_read_b128 v[220:223], v158 offset:56320
	global_load_lds_dwordx4 v[224:225], off
	s_add_i32 m0, s34, 0x2000
	s_add_u32 s30, s30, 0x40080
	v_lshl_add_u64 v[224:225], v[226:227], 0, s[16:17]
	s_addc_u32 s31, s31, 0
	s_add_i32 s34, s70, s3
	global_load_lds_dwordx4 v[224:225], off
	v_lshl_add_u64 v[224:225], s[30:31], 0, v[134:135]
	s_mov_b32 m0, s34
	s_nop 0
	global_load_lds_dwordx4 v[224:225], off
	v_lshl_add_u64 v[224:225], s[30:31], 0, v[130:131]
	s_add_i32 m0, s34, 0x2000
	s_nop 0
	global_load_lds_dwordx4 v[224:225], off
	v_lshl_add_u64 v[224:225], v[228:229], 0, s[16:17]
	s_mov_b32 m0, s43
	s_nop 0
	global_load_lds_dwordx4 v[224:225], off
	v_lshl_add_u64 v[224:225], v[230:231], 0, s[16:17]
	s_mov_b32 m0, s44
	s_nop 0
	global_load_lds_dwordx4 v[224:225], off
	s_waitcnt vmcnt(8)
	s_waitcnt lgkmcnt(0)
	s_barrier
	s_setprio 1
	s_waitcnt lgkmcnt(0)
	v_mfma_f32_16x16x32_bf16 v[62:65], v[148:151], v[192:195], v[62:65]
	v_mfma_f32_16x16x32_bf16 v[58:61], v[168:171], v[192:195], v[58:61]
	v_mfma_f32_16x16x32_bf16 v[46:49], v[148:151], v[200:203], v[46:49]
	v_mfma_f32_16x16x32_bf16 v[42:45], v[168:171], v[200:203], v[42:45]
	v_mfma_f32_16x16x32_bf16 v[30:33], v[148:151], v[208:211], v[30:33]
	v_mfma_f32_16x16x32_bf16 v[26:29], v[168:171], v[208:211], v[26:29]
	v_mfma_f32_16x16x32_bf16 v[14:17], v[148:151], v[216:219], v[14:17]
	v_mfma_f32_16x16x32_bf16 v[10:13], v[168:171], v[216:219], v[10:13]
	v_mfma_f32_16x16x32_bf16 v[62:65], v[164:167], v[196:199], v[62:65]
	v_mfma_f32_16x16x32_bf16 v[58:61], v[172:175], v[196:199], v[58:61]
	v_mfma_f32_16x16x32_bf16 v[46:49], v[164:167], v[204:207], v[46:49]
	v_mfma_f32_16x16x32_bf16 v[42:45], v[172:175], v[204:207], v[42:45]
	v_mfma_f32_16x16x32_bf16 v[30:33], v[164:167], v[212:215], v[30:33]
	v_mfma_f32_16x16x32_bf16 v[26:29], v[172:175], v[212:215], v[26:29]
	v_mfma_f32_16x16x32_bf16 v[14:17], v[164:167], v[220:223], v[14:17]
	v_mfma_f32_16x16x32_bf16 v[10:13], v[172:175], v[220:223], v[10:13]
	s_setprio 0
	s_setprio 1
	v_mfma_f32_16x16x32_bf16 v[54:57], v[176:179], v[192:195], v[54:57]
	v_mfma_f32_16x16x32_bf16 v[50:53], v[184:187], v[192:195], v[50:53]
	v_mfma_f32_16x16x32_bf16 v[38:41], v[176:179], v[200:203], v[38:41]
	v_mfma_f32_16x16x32_bf16 v[34:37], v[184:187], v[200:203], v[34:37]
	v_mfma_f32_16x16x32_bf16 v[22:25], v[176:179], v[208:211], v[22:25]
	v_mfma_f32_16x16x32_bf16 v[18:21], v[184:187], v[208:211], v[18:21]
	v_mfma_f32_16x16x32_bf16 v[6:9], v[176:179], v[216:219], v[6:9]
	v_mfma_f32_16x16x32_bf16 v[2:5], v[184:187], v[216:219], v[2:5]
	v_mfma_f32_16x16x32_bf16 v[54:57], v[180:183], v[196:199], v[54:57]
	v_mfma_f32_16x16x32_bf16 v[50:53], v[188:191], v[196:199], v[50:53]
	v_mfma_f32_16x16x32_bf16 v[38:41], v[180:183], v[204:207], v[38:41]
	v_mfma_f32_16x16x32_bf16 v[34:37], v[188:191], v[204:207], v[34:37]
	v_mfma_f32_16x16x32_bf16 v[22:25], v[180:183], v[212:215], v[22:25]
	v_mfma_f32_16x16x32_bf16 v[18:21], v[188:191], v[212:215], v[18:21]
	v_mfma_f32_16x16x32_bf16 v[6:9], v[180:183], v[220:223], v[6:9]
	v_mfma_f32_16x16x32_bf16 v[2:5], v[188:191], v[220:223], v[2:5]
	s_setprio 0
	s_barrier
	s_add_i32 s68, s68, 2
	s_add_u32 s28, s28, 0x100
	s_addc_u32 s29, s29, 0
	s_add_u32 s66, s66, 0x100
	s_addc_u32 s67, s67, 0
	s_cmp_gt_u32 s68, 13
	s_cbranch_scc1 .Lpeel_done_p6

; #define PG8_BAR __builtin_amdgcn_s_barrier()
; template <class Epi, class Sched, bool ALIGN_EPI = false, bool SP2 = false, bool AGM = false  >
; __device__ __forceinline__ void gemm_phase(PG8_LAS unsigned char* lds, const Gemm g, const Sched& S, const Epi& E) {
;     ...
;         if constexpr (ALIGN_EPI) { if (wr == 0) PG8_BAR; }
;         if constexpr (!Epi::AFTER_DRAIN) { E(acc, cur, wr, wc, fr, fq); S.done(cur); }
;         if (!has_next) break;
.Lpeel_done_p6:
	s_and_b64 vcc, exec, s[18:19]
	s_cbranch_vccz .LBB0_880
	s_barrier
